# EPI_RES epilogues of all four residual GEMMs re-scheduled (loads of tile t+1 in flight while tile t is stored), plus earlier DA and norm edits
# speedup vs baseline: 1.0143x; 1.0143x over previous
.LBB0_378:
	s_waitcnt lgkmcnt(0)
	s_lshl_b32 s24, s61, 8
	s_add_i32 s70, s24, s37
	s_lshl_b64 s[2:3], s[2:3], s78
	s_lshl_b64 s[76:77], s[76:77], 10
	s_add_u32 s2, s76, s2
	s_addc_u32 s3, s77, s3
	s_lshl_b64 s[2:3], s[2:3], 2
	s_add_u32 s24, s74, s2
	s_addc_u32 s75, s75, s3
	s_ashr_i32 s71, s70, 31
	s_lshl_b64 s[70:71], s[70:71], 2
	s_add_u32 s74, s24, s70
	s_addc_u32 s75, s75, s71
	s_add_u32 s2, s72, s2
	s_addc_u32 s3, s73, s3
	s_add_u32 s2, s2, s70
	s_addc_u32 s3, s3, s71
	s_add_u32 s24, s20, s62
	s_addc_u32 s63, s21, s63
	s_add_u32 s62, s24, s70
	s_addc_u32 s63, s63, s71
	v_lshl_add_u64 v[128:129], s[62:63], 0, v[178:179]
	s_mov_b64 s[62:63], 0x2000
	v_lshl_add_u64 v[130:131], s[2:3], 0, v[178:179]
	s_movk_i32 s2, 0x2000
	v_lshl_add_u64 v[132:133], v[128:129], 0, s[62:63]
	v_add_co_u32_e32 v128, vcc, s2, v128
	v_lshl_add_u64 v[134:135], s[74:75], 0, v[178:179]
	v_mov_b32_e32 v185, v179
	s_nop 1
	v_addc_co_u32_e32 v129, vcc, 0, v129, vcc
	v_lshl_add_u64 v[136:137], v[134:135], 0, v[184:185]
	global_load_dwordx4 v[138:141], v[128:129], off
	global_load_dwordx4 v[142:145], v[136:137], off
	v_lshl_add_u64 v[146:147], v[130:131], 0, v[184:185]
	v_mov_b32_e32 v187, v179
	v_mov_b32_e32 v189, v179
	v_mov_b32_e32 v191, v179
	s_add_i32 s65, s65, 1
	s_cmp_eq_u32 s65, s35
	v_lshl_add_u64 v[148:149], v[134:135], 0, v[186:187]
	global_load_dwordx4 v[150:153], v[128:129], off
	global_load_dwordx4 v[154:157], v[148:149], off
	v_lshl_add_u64 v[158:159], v[130:131], 0, v[186:187]
	v_lshl_add_u64 v[160:161], v[134:135], 0, v[188:189]
	global_load_dwordx4 v[162:165], v[128:129], off
	global_load_dwordx4 v[166:169], v[160:161], off
	v_lshl_add_u64 v[170:171], v[130:131], 0, v[188:189]
	v_lshl_add_u64 v[172:173], v[134:135], 0, v[190:191]
	global_load_dwordx4 v[216:219], v[128:129], off
	global_load_dwordx4 v[220:223], v[172:173], off
	v_lshl_add_u64 v[174:175], v[130:131], 0, v[190:191]
	ds_write_b128 v211, v[112:115]
	ds_write_b128 v211, v[116:119] offset:32
	ds_write_b128 v211, v[120:123] offset:64
	ds_write_b128 v211, v[124:127] offset:96
	ds_read_b128 v[112:115], v212
	ds_read_b128 v[116:119], v213
	ds_read_b128 v[120:123], v214
	ds_read_b128 v[124:127], v215
	s_waitcnt vmcnt(6) lgkmcnt(3)
	v_pk_fma_f32 v[112:113], v[112:113], v[138:139], v[142:143]
	v_pk_fma_f32 v[114:115], v[114:115], v[140:141], v[144:145]
	global_store_dwordx4 v[146:147], v[112:115], off
	s_waitcnt vmcnt(5) lgkmcnt(2)
	v_pk_fma_f32 v[116:117], v[116:117], v[150:151], v[154:155]
	v_pk_fma_f32 v[118:119], v[118:119], v[152:153], v[156:157]
	global_store_dwordx4 v[158:159], v[116:119], off
	s_waitcnt vmcnt(4) lgkmcnt(1)
	v_pk_fma_f32 v[120:121], v[120:121], v[162:163], v[166:167]
	v_pk_fma_f32 v[122:123], v[122:123], v[164:165], v[168:169]
	global_store_dwordx4 v[170:171], v[120:123], off
	s_waitcnt vmcnt(3) lgkmcnt(0)
	v_pk_fma_f32 v[124:125], v[124:125], v[216:217], v[220:221]
	v_pk_fma_f32 v[126:127], v[126:127], v[218:219], v[222:223]
	global_store_dwordx4 v[174:175], v[124:127], off
	v_lshl_add_u64 v[112:113], v[134:135], 0, s[8:9]
	v_lshl_add_u64 v[114:115], v[112:113], 0, v[184:185]
	global_load_dwordx4 v[118:121], v[128:129], off
	global_load_dwordx4 v[114:117], v[114:115], off
	v_lshl_add_u64 v[122:123], v[130:131], 0, s[8:9]
	v_lshl_add_u64 v[124:125], v[122:123], 0, v[184:185]
	v_lshl_add_u64 v[138:139], v[112:113], 0, v[186:187]
	global_load_dwordx4 v[142:145], v[128:129], off
	global_load_dwordx4 v[138:141], v[138:139], off
	v_lshl_add_u64 v[126:127], v[122:123], 0, v[186:187]
	v_lshl_add_u64 v[150:151], v[112:113], 0, v[188:189]
	global_load_dwordx4 v[154:157], v[128:129], off
	global_load_dwordx4 v[150:153], v[150:151], off
	v_lshl_add_u64 v[162:163], v[122:123], 0, v[188:189]
	v_lshl_add_u64 v[164:165], v[112:113], 0, v[190:191]
	global_load_dwordx4 v[216:219], v[128:129], off
	global_load_dwordx4 v[164:167], v[164:165], off
	v_lshl_add_u64 v[168:169], v[122:123], 0, v[190:191]
	ds_write_b128 v211, v[96:99]
	ds_write_b128 v211, v[100:103] offset:32
	ds_write_b128 v211, v[104:107] offset:64
	ds_write_b128 v211, v[108:111] offset:96
	ds_read_b128 v[96:99], v212
	ds_read_b128 v[100:103], v213
	ds_read_b128 v[104:107], v214
	ds_read_b128 v[108:111], v215
	s_waitcnt vmcnt(6) lgkmcnt(3)
	v_pk_fma_f32 v[96:97], v[96:97], v[118:119], v[114:115]
	v_pk_fma_f32 v[98:99], v[98:99], v[120:121], v[116:117]
	global_store_dwordx4 v[124:125], v[96:99], off
	s_waitcnt vmcnt(5) lgkmcnt(2)
	v_pk_fma_f32 v[100:101], v[100:101], v[142:143], v[138:139]
	v_pk_fma_f32 v[102:103], v[102:103], v[144:145], v[140:141]
	global_store_dwordx4 v[126:127], v[100:103], off
	s_waitcnt vmcnt(4) lgkmcnt(1)
	v_pk_fma_f32 v[104:105], v[104:105], v[154:155], v[150:151]
	v_pk_fma_f32 v[106:107], v[106:107], v[156:157], v[152:153]
	global_store_dwordx4 v[162:163], v[104:107], off
	s_waitcnt vmcnt(3) lgkmcnt(0)
	v_pk_fma_f32 v[108:109], v[108:109], v[216:217], v[164:165]
	v_pk_fma_f32 v[110:111], v[110:111], v[218:219], v[166:167]
	global_store_dwordx4 v[168:169], v[108:111], off
	global_load_dwordx4 v[96:99], v[132:133], off offset:128
	global_load_dwordx4 v[100:103], v[136:137], off offset:128
	global_load_dwordx4 v[104:107], v[132:133], off offset:128
	global_load_dwordx4 v[108:111], v[148:149], off offset:128
	global_load_dwordx4 v[112:115], v[132:133], off offset:128
	global_load_dwordx4 v[116:119], v[160:161], off offset:128
	global_load_dwordx4 v[120:123], v[132:133], off offset:128
	global_load_dwordx4 v[124:127], v[172:173], off offset:128
	ds_write_b128 v211, v[80:83]
	ds_write_b128 v211, v[84:87] offset:32
	ds_write_b128 v211, v[88:91] offset:64
	ds_write_b128 v211, v[92:95] offset:96
	ds_read_b128 v[80:83], v212
	ds_read_b128 v[84:87], v213
	ds_read_b128 v[88:91], v214
	ds_read_b128 v[92:95], v215
	s_mov_b64 s[2:3], 0x20080
	v_lshl_add_u64 v[128:129], v[134:135], 0, s[2:3]
	v_lshl_add_u64 v[138:139], v[128:129], 0, v[184:185]
	global_load_dwordx4 v[142:145], v[132:133], off offset:128
	global_load_dwordx4 v[138:141], v[138:139], off
	v_lshl_add_u64 v[150:151], v[130:131], 0, s[2:3]
	v_lshl_add_u64 v[152:153], v[150:151], 0, v[184:185]
	v_lshl_add_u64 v[154:155], v[128:129], 0, v[186:187]
	global_load_dwordx4 v[162:165], v[132:133], off offset:128
	global_load_dwordx4 v[154:157], v[154:155], off
	v_lshl_add_u64 v[166:167], v[150:151], 0, v[186:187]
	v_lshl_add_u64 v[216:217], v[128:129], 0, v[188:189]
	global_load_dwordx4 v[220:223], v[132:133], off offset:128
	global_load_dwordx4 v[216:219], v[216:217], off
	v_lshl_add_u64 v[168:169], v[150:151], 0, v[188:189]
	v_lshl_add_u64 v[224:225], v[128:129], 0, v[190:191]
	global_load_dwordx4 v[240:243], v[132:133], off offset:128
	global_load_dwordx4 v[224:227], v[224:225], off
	v_lshl_add_u64 v[244:245], v[150:151], 0, v[190:191]
	s_waitcnt vmcnt(14) lgkmcnt(3)
	v_pk_fma_f32 v[80:81], v[80:81], v[96:97], v[100:101]
	v_pk_fma_f32 v[82:83], v[82:83], v[98:99], v[102:103]
	global_store_dwordx4 v[146:147], v[80:83], off offset:128
	s_waitcnt vmcnt(13) lgkmcnt(2)
	v_pk_fma_f32 v[84:85], v[84:85], v[104:105], v[108:109]
	v_pk_fma_f32 v[86:87], v[86:87], v[106:107], v[110:111]
	global_store_dwordx4 v[158:159], v[84:87], off offset:128
	s_waitcnt vmcnt(12) lgkmcnt(1)
	v_pk_fma_f32 v[88:89], v[88:89], v[112:113], v[116:117]
	v_pk_fma_f32 v[90:91], v[90:91], v[114:115], v[118:119]
	global_store_dwordx4 v[170:171], v[88:91], off offset:128
	s_waitcnt vmcnt(11) lgkmcnt(0)
	v_pk_fma_f32 v[92:93], v[92:93], v[120:121], v[124:125]
	v_pk_fma_f32 v[94:95], v[94:95], v[122:123], v[126:127]
	global_store_dwordx4 v[174:175], v[92:95], off offset:128
	ds_write_b128 v211, v[64:67]
	ds_write_b128 v211, v[68:71] offset:32
	ds_write_b128 v211, v[72:75] offset:64
	ds_write_b128 v211, v[76:79] offset:96
	ds_read_b128 v[64:67], v212
	ds_read_b128 v[68:71], v213
	ds_read_b128 v[72:75], v214
	ds_read_b128 v[76:79], v215
	global_load_dwordx4 v[80:83], v[132:133], off offset:256
	global_load_dwordx4 v[84:87], v[136:137], off offset:256
	global_load_dwordx4 v[88:91], v[132:133], off offset:256
	global_load_dwordx4 v[92:95], v[148:149], off offset:256
	global_load_dwordx4 v[96:99], v[132:133], off offset:256
	global_load_dwordx4 v[100:103], v[160:161], off offset:256
	global_load_dwordx4 v[104:107], v[132:133], off offset:256
	global_load_dwordx4 v[108:111], v[172:173], off offset:256
	s_waitcnt vmcnt(18) lgkmcnt(3)
	v_pk_fma_f32 v[64:65], v[64:65], v[142:143], v[138:139]
	v_pk_fma_f32 v[66:67], v[66:67], v[144:145], v[140:141]
	global_store_dwordx4 v[152:153], v[64:67], off
	s_waitcnt vmcnt(17) lgkmcnt(2)
	v_pk_fma_f32 v[68:69], v[68:69], v[162:163], v[154:155]
	v_pk_fma_f32 v[70:71], v[70:71], v[164:165], v[156:157]
	global_store_dwordx4 v[166:167], v[68:71], off
	s_waitcnt vmcnt(16) lgkmcnt(1)
	v_pk_fma_f32 v[72:73], v[72:73], v[220:221], v[216:217]
	v_pk_fma_f32 v[74:75], v[74:75], v[222:223], v[218:219]
	global_store_dwordx4 v[168:169], v[72:75], off
	s_waitcnt vmcnt(15) lgkmcnt(0)
	v_pk_fma_f32 v[76:77], v[76:77], v[240:241], v[224:225]
	v_pk_fma_f32 v[78:79], v[78:79], v[242:243], v[226:227]
	global_store_dwordx4 v[244:245], v[76:79], off
	ds_write_b128 v211, v[48:51]
	ds_write_b128 v211, v[52:55] offset:32
	ds_write_b128 v211, v[56:59] offset:64
	ds_write_b128 v211, v[60:63] offset:96
	ds_read_b128 v[48:51], v212
	ds_read_b128 v[52:55], v213
	ds_read_b128 v[56:59], v214
	ds_read_b128 v[60:63], v215
	v_lshl_add_u64 v[64:65], v[134:135], 0, s[54:55]
	v_lshl_add_u64 v[66:67], v[64:65], 0, v[184:185]
	global_load_dwordx4 v[70:73], v[132:133], off offset:256
	global_load_dwordx4 v[66:69], v[66:67], off
	v_lshl_add_u64 v[74:75], v[130:131], 0, s[54:55]
	v_lshl_add_u64 v[76:77], v[74:75], 0, v[184:185]
	v_lshl_add_u64 v[112:113], v[64:65], 0, v[186:187]
	global_load_dwordx4 v[116:119], v[132:133], off offset:256
	global_load_dwordx4 v[112:115], v[112:113], off
	v_lshl_add_u64 v[78:79], v[74:75], 0, v[186:187]
	v_lshl_add_u64 v[120:121], v[64:65], 0, v[188:189]
	global_load_dwordx4 v[124:127], v[132:133], off offset:256
	global_load_dwordx4 v[120:123], v[120:121], off
	v_lshl_add_u64 v[128:129], v[74:75], 0, v[188:189]
	v_lshl_add_u64 v[138:139], v[64:65], 0, v[190:191]
	global_load_dwordx4 v[142:145], v[132:133], off offset:256
	global_load_dwordx4 v[138:141], v[138:139], off
	v_lshl_add_u64 v[150:151], v[74:75], 0, v[190:191]
	s_waitcnt vmcnt(18) lgkmcnt(3)
	v_pk_fma_f32 v[48:49], v[48:49], v[80:81], v[84:85]
	v_pk_fma_f32 v[50:51], v[50:51], v[82:83], v[86:87]
	global_store_dwordx4 v[146:147], v[48:51], off offset:256
	s_waitcnt vmcnt(17) lgkmcnt(2)
	v_pk_fma_f32 v[52:53], v[52:53], v[88:89], v[92:93]
	v_pk_fma_f32 v[54:55], v[54:55], v[90:91], v[94:95]
	global_store_dwordx4 v[158:159], v[52:55], off offset:256
	s_waitcnt vmcnt(16) lgkmcnt(1)
	v_pk_fma_f32 v[56:57], v[56:57], v[96:97], v[100:101]
	v_pk_fma_f32 v[58:59], v[58:59], v[98:99], v[102:103]
	global_store_dwordx4 v[170:171], v[56:59], off offset:256
	s_waitcnt vmcnt(15) lgkmcnt(0)
	v_pk_fma_f32 v[60:61], v[60:61], v[104:105], v[108:109]
	v_pk_fma_f32 v[62:63], v[62:63], v[106:107], v[110:111]
	global_store_dwordx4 v[174:175], v[60:63], off offset:256
	ds_write_b128 v211, v[32:35]
	ds_write_b128 v211, v[36:39] offset:32
	ds_write_b128 v211, v[40:43] offset:64
	ds_write_b128 v211, v[44:47] offset:96
	ds_read_b128 v[32:35], v212
	ds_read_b128 v[36:39], v213
	ds_read_b128 v[40:43], v214
	ds_read_b128 v[44:47], v215
	global_load_dwordx4 v[48:51], v[132:133], off offset:384
	global_load_dwordx4 v[52:55], v[136:137], off offset:384
	global_load_dwordx4 v[56:59], v[132:133], off offset:384
	global_load_dwordx4 v[60:63], v[148:149], off offset:384
	global_load_dwordx4 v[80:83], v[132:133], off offset:384
	global_load_dwordx4 v[84:87], v[160:161], off offset:384
	global_load_dwordx4 v[88:91], v[132:133], off offset:384
	global_load_dwordx4 v[92:95], v[172:173], off offset:384
	s_waitcnt vmcnt(18) lgkmcnt(3)
	v_pk_fma_f32 v[32:33], v[32:33], v[70:71], v[66:67]
	v_pk_fma_f32 v[34:35], v[34:35], v[72:73], v[68:69]
	global_store_dwordx4 v[76:77], v[32:35], off
	s_waitcnt vmcnt(17) lgkmcnt(2)
	v_pk_fma_f32 v[36:37], v[36:37], v[116:117], v[112:113]
	v_pk_fma_f32 v[38:39], v[38:39], v[118:119], v[114:115]
	global_store_dwordx4 v[78:79], v[36:39], off
	s_waitcnt vmcnt(16) lgkmcnt(1)
	v_pk_fma_f32 v[40:41], v[40:41], v[124:125], v[120:121]
	v_pk_fma_f32 v[42:43], v[42:43], v[126:127], v[122:123]
	global_store_dwordx4 v[128:129], v[40:43], off
	s_waitcnt vmcnt(15) lgkmcnt(0)
	v_pk_fma_f32 v[44:45], v[44:45], v[142:143], v[138:139]
	v_pk_fma_f32 v[46:47], v[46:47], v[144:145], v[140:141]
	global_store_dwordx4 v[150:151], v[44:47], off
	ds_write_b128 v211, v[16:19]
	ds_write_b128 v211, v[20:23] offset:32
	ds_write_b128 v211, v[24:27] offset:64
	ds_write_b128 v211, v[28:31] offset:96
	ds_read_b128 v[16:19], v212
	ds_read_b128 v[20:23], v213
	ds_read_b128 v[24:27], v214
	ds_read_b128 v[28:31], v215
	v_lshl_add_u64 v[32:33], v[134:135], 0, s[58:59]
	v_lshl_add_u64 v[34:35], v[32:33], 0, v[184:185]
	global_load_dwordx4 v[38:41], v[132:133], off offset:384
	global_load_dwordx4 v[34:37], v[34:35], off
	v_lshl_add_u64 v[42:43], v[130:131], 0, s[58:59]
	v_lshl_add_u64 v[44:45], v[42:43], 0, v[184:185]
	v_lshl_add_u64 v[64:65], v[32:33], 0, v[186:187]
	global_load_dwordx4 v[68:71], v[132:133], off offset:384
	global_load_dwordx4 v[64:67], v[64:65], off
	v_lshl_add_u64 v[46:47], v[42:43], 0, v[186:187]
	v_lshl_add_u64 v[72:73], v[32:33], 0, v[188:189]
	global_load_dwordx4 v[76:79], v[132:133], off offset:384
	global_load_dwordx4 v[72:75], v[72:73], off
	v_lshl_add_u64 v[96:97], v[42:43], 0, v[188:189]
	v_lshl_add_u64 v[98:99], v[32:33], 0, v[190:191]
	global_load_dwordx4 v[102:105], v[132:133], off offset:384
	global_load_dwordx4 v[98:101], v[98:99], off
	v_lshl_add_u64 v[106:107], v[42:43], 0, v[190:191]
	s_waitcnt vmcnt(18) lgkmcnt(3)
	v_pk_fma_f32 v[16:17], v[16:17], v[48:49], v[52:53]
	v_pk_fma_f32 v[18:19], v[18:19], v[50:51], v[54:55]
	global_store_dwordx4 v[146:147], v[16:19], off offset:384
	s_waitcnt vmcnt(17) lgkmcnt(2)
	v_pk_fma_f32 v[20:21], v[20:21], v[56:57], v[60:61]
	v_pk_fma_f32 v[22:23], v[22:23], v[58:59], v[62:63]
	global_store_dwordx4 v[158:159], v[20:23], off offset:384
	s_waitcnt vmcnt(16) lgkmcnt(1)
	v_pk_fma_f32 v[24:25], v[24:25], v[80:81], v[84:85]
	v_pk_fma_f32 v[26:27], v[26:27], v[82:83], v[86:87]
	global_store_dwordx4 v[170:171], v[24:27], off offset:384
	s_waitcnt vmcnt(15) lgkmcnt(0)
	v_pk_fma_f32 v[28:29], v[28:29], v[88:89], v[92:93]
	v_pk_fma_f32 v[30:31], v[30:31], v[90:91], v[94:95]
	global_store_dwordx4 v[174:175], v[28:31], off offset:384
	ds_write_b128 v211, v[0:3]
	ds_write_b128 v211, v[4:7] offset:32
	ds_write_b128 v211, v[8:11] offset:64
	ds_write_b128 v211, v[12:15] offset:96
	ds_read_b128 v[0:3], v212
	ds_read_b128 v[4:7], v213
	ds_read_b128 v[8:11], v214
	ds_read_b128 v[12:15], v215
	s_waitcnt vmcnt(10) lgkmcnt(3)
	v_pk_fma_f32 v[0:1], v[0:1], v[38:39], v[34:35]
	v_pk_fma_f32 v[2:3], v[2:3], v[40:41], v[36:37]
	global_store_dwordx4 v[44:45], v[0:3], off
	s_waitcnt vmcnt(9) lgkmcnt(2)
	v_pk_fma_f32 v[4:5], v[4:5], v[68:69], v[64:65]
	v_pk_fma_f32 v[6:7], v[6:7], v[70:71], v[66:67]
	global_store_dwordx4 v[46:47], v[4:7], off
	s_waitcnt vmcnt(8) lgkmcnt(1)
	v_pk_fma_f32 v[8:9], v[8:9], v[76:77], v[72:73]
	v_pk_fma_f32 v[10:11], v[10:11], v[78:79], v[74:75]
	global_store_dwordx4 v[96:97], v[8:11], off
	s_waitcnt vmcnt(7) lgkmcnt(0)
	v_pk_fma_f32 v[12:13], v[12:13], v[102:103], v[98:99]
	v_pk_fma_f32 v[14:15], v[14:15], v[104:105], v[100:101]
	global_store_dwordx4 v[106:107], v[12:15], off
	s_waitcnt lgkmcnt(0)
	s_barrier
	s_cbranch_scc1 .LBB0_434

.LBB0_732:
	s_waitcnt lgkmcnt(0)
	s_lshl_b32 s24, s31, 8
	s_add_i32 s54, s24, s37
	s_lshl_b64 s[2:3], s[2:3], s60
	s_lshl_b64 s[58:59], s[58:59], 12
	s_add_u32 s24, s56, s58
	s_addc_u32 s55, s57, s59
	s_lshl_b64 s[2:3], s[2:3], 2
	s_add_u32 s24, s24, s2
	s_addc_u32 s56, s55, s3
	s_ashr_i32 s55, s54, 31
	s_lshl_b64 s[2:3], s[54:55], 2
	s_add_u32 s54, s24, s2
	s_addc_u32 s55, s56, s3
	s_add_u32 s24, s20, s52
	s_addc_u32 s52, s21, s53
	s_add_u32 s2, s24, s2
	s_addc_u32 s3, s52, s3
	v_lshl_add_u64 v[128:129], s[2:3], 0, v[178:179]
	s_mov_b64 s[2:3], 0x5000
	v_lshl_add_u64 v[130:131], v[128:129], 0, s[2:3]
	s_movk_i32 s2, 0x5000
	v_add_co_u32_e32 v132, vcc, s2, v128
	v_lshl_add_u64 v[134:135], s[54:55], 0, v[178:179]
	v_mov_b32_e32 v185, v179
	s_nop 1
	v_addc_co_u32_e32 v133, vcc, 0, v129, vcc
	v_lshl_add_u64 v[136:137], v[134:135], 0, v[184:185]
	global_load_dwordx4 v[138:141], v[132:133], off
	global_load_dwordx4 v[142:145], v[136:137], off
	v_mov_b32_e32 v187, v179
	v_mov_b32_e32 v189, v179
	v_mov_b32_e32 v191, v179
	s_add_i32 s70, s70, 1
	s_cmp_eq_u32 s70, s35
	v_lshl_add_u64 v[128:129], v[134:135], 0, v[186:187]
	global_load_dwordx4 v[146:149], v[132:133], off
	global_load_dwordx4 v[150:153], v[128:129], off
	v_lshl_add_u64 v[154:155], v[134:135], 0, v[188:189]
	global_load_dwordx4 v[156:159], v[132:133], off
	global_load_dwordx4 v[160:163], v[154:155], off
	v_lshl_add_u64 v[164:165], v[134:135], 0, v[190:191]
	global_load_dwordx4 v[166:169], v[132:133], off
	global_load_dwordx4 v[170:173], v[164:165], off
	ds_write_b128 v211, v[112:115]
	ds_write_b128 v211, v[116:119] offset:32
	ds_write_b128 v211, v[120:123] offset:64
	ds_write_b128 v211, v[124:127] offset:96
	ds_read_b128 v[112:115], v212
	ds_read_b128 v[116:119], v213
	ds_read_b128 v[120:123], v214
	ds_read_b128 v[124:127], v215
	s_waitcnt vmcnt(6) lgkmcnt(3)
	v_pk_fma_f32 v[112:113], v[112:113], v[138:139], v[142:143]
	v_pk_fma_f32 v[114:115], v[114:115], v[140:141], v[144:145]
	global_store_dwordx4 v[136:137], v[112:115], off
	s_waitcnt vmcnt(5) lgkmcnt(2)
	v_pk_fma_f32 v[116:117], v[116:117], v[146:147], v[150:151]
	v_pk_fma_f32 v[118:119], v[118:119], v[148:149], v[152:153]
	global_store_dwordx4 v[128:129], v[116:119], off
	s_waitcnt vmcnt(4) lgkmcnt(1)
	v_pk_fma_f32 v[120:121], v[120:121], v[156:157], v[160:161]
	v_pk_fma_f32 v[122:123], v[122:123], v[158:159], v[162:163]
	global_store_dwordx4 v[154:155], v[120:123], off
	s_waitcnt vmcnt(3) lgkmcnt(0)
	v_pk_fma_f32 v[124:125], v[124:125], v[166:167], v[170:171]
	v_pk_fma_f32 v[126:127], v[126:127], v[168:169], v[172:173]
	global_store_dwordx4 v[164:165], v[124:127], off
	s_mov_b64 s[2:3], 0x20000
	v_lshl_add_u64 v[112:113], v[134:135], 0, s[2:3]
	v_lshl_add_u64 v[114:115], v[112:113], 0, v[184:185]
	global_load_dwordx4 v[116:119], v[132:133], off
	global_load_dwordx4 v[120:123], v[114:115], off
	v_lshl_add_u64 v[124:125], v[112:113], 0, v[186:187]
	global_load_dwordx4 v[138:141], v[132:133], off
	global_load_dwordx4 v[142:145], v[124:125], off
	v_lshl_add_u64 v[126:127], v[112:113], 0, v[188:189]
	global_load_dwordx4 v[146:149], v[132:133], off
	global_load_dwordx4 v[150:153], v[126:127], off
	v_lshl_add_u64 v[112:113], v[112:113], 0, v[190:191]
	global_load_dwordx4 v[156:159], v[132:133], off
	global_load_dwordx4 v[160:163], v[112:113], off
	ds_write_b128 v211, v[96:99]
	ds_write_b128 v211, v[100:103] offset:32
	ds_write_b128 v211, v[104:107] offset:64
	ds_write_b128 v211, v[108:111] offset:96
	ds_read_b128 v[96:99], v212
	ds_read_b128 v[100:103], v213
	ds_read_b128 v[104:107], v214
	ds_read_b128 v[108:111], v215
	global_load_dwordx4 v[166:169], v[130:131], off offset:128
	global_load_dwordx4 v[170:173], v[136:137], off offset:128
	global_load_dwordx4 v[216:219], v[130:131], off offset:128
	global_load_dwordx4 v[220:223], v[128:129], off offset:128
	global_load_dwordx4 v[224:227], v[130:131], off offset:128
	global_load_dwordx4 v[240:243], v[154:155], off offset:128
	global_load_dwordx4 v[244:247], v[130:131], off offset:128
	global_load_dwordx4 v[248:251], v[164:165], off offset:128
	s_waitcnt vmcnt(14) lgkmcnt(3)
	v_pk_fma_f32 v[96:97], v[96:97], v[116:117], v[120:121]
	v_pk_fma_f32 v[98:99], v[98:99], v[118:119], v[122:123]
	global_store_dwordx4 v[114:115], v[96:99], off
	s_waitcnt vmcnt(13) lgkmcnt(2)
	v_pk_fma_f32 v[100:101], v[100:101], v[138:139], v[142:143]
	v_pk_fma_f32 v[102:103], v[102:103], v[140:141], v[144:145]
	global_store_dwordx4 v[124:125], v[100:103], off
	s_waitcnt vmcnt(12) lgkmcnt(1)
	v_pk_fma_f32 v[104:105], v[104:105], v[146:147], v[150:151]
	v_pk_fma_f32 v[106:107], v[106:107], v[148:149], v[152:153]
	global_store_dwordx4 v[126:127], v[104:107], off
	s_waitcnt vmcnt(11) lgkmcnt(0)
	v_pk_fma_f32 v[108:109], v[108:109], v[156:157], v[160:161]
	v_pk_fma_f32 v[110:111], v[110:111], v[158:159], v[162:163]
	global_store_dwordx4 v[112:113], v[108:111], off
	ds_write_b128 v211, v[80:83]
	ds_write_b128 v211, v[84:87] offset:32
	ds_write_b128 v211, v[88:91] offset:64
	ds_write_b128 v211, v[92:95] offset:96
	ds_read_b128 v[80:83], v212
	ds_read_b128 v[84:87], v213
	ds_read_b128 v[88:91], v214
	ds_read_b128 v[92:95], v215
	s_mov_b64 s[2:3], 0x20080
	v_lshl_add_u64 v[96:97], v[134:135], 0, s[2:3]
	v_lshl_add_u64 v[98:99], v[96:97], 0, v[184:185]
	global_load_dwordx4 v[100:103], v[130:131], off offset:128
	global_load_dwordx4 v[104:107], v[98:99], off
	v_lshl_add_u64 v[108:109], v[96:97], 0, v[186:187]
	global_load_dwordx4 v[110:113], v[130:131], off offset:128
	global_load_dwordx4 v[114:117], v[108:109], off
	v_lshl_add_u64 v[118:119], v[96:97], 0, v[188:189]
	global_load_dwordx4 v[120:123], v[130:131], off offset:128
	global_load_dwordx4 v[124:127], v[118:119], off
	v_lshl_add_u64 v[96:97], v[96:97], 0, v[190:191]
	global_load_dwordx4 v[138:141], v[130:131], off offset:128
	global_load_dwordx4 v[142:145], v[96:97], off
	s_waitcnt vmcnt(18) lgkmcnt(3)
	v_pk_fma_f32 v[80:81], v[80:81], v[166:167], v[170:171]
	v_pk_fma_f32 v[82:83], v[82:83], v[168:169], v[172:173]
	global_store_dwordx4 v[136:137], v[80:83], off offset:128
	s_waitcnt vmcnt(17) lgkmcnt(2)
	v_pk_fma_f32 v[84:85], v[84:85], v[216:217], v[220:221]
	v_pk_fma_f32 v[86:87], v[86:87], v[218:219], v[222:223]
	global_store_dwordx4 v[128:129], v[84:87], off offset:128
	s_waitcnt vmcnt(16) lgkmcnt(1)
	v_pk_fma_f32 v[88:89], v[88:89], v[224:225], v[240:241]
	v_pk_fma_f32 v[90:91], v[90:91], v[226:227], v[242:243]
	global_store_dwordx4 v[154:155], v[88:91], off offset:128
	s_waitcnt vmcnt(15) lgkmcnt(0)
	v_pk_fma_f32 v[92:93], v[92:93], v[244:245], v[248:249]
	v_pk_fma_f32 v[94:95], v[94:95], v[246:247], v[250:251]
	global_store_dwordx4 v[164:165], v[92:95], off offset:128
	ds_write_b128 v211, v[64:67]
	ds_write_b128 v211, v[68:71] offset:32
	ds_write_b128 v211, v[72:75] offset:64
	ds_write_b128 v211, v[76:79] offset:96
	ds_read_b128 v[64:67], v212
	ds_read_b128 v[68:71], v213
	ds_read_b128 v[72:75], v214
	ds_read_b128 v[76:79], v215
	global_load_dwordx4 v[80:83], v[130:131], off offset:256
	global_load_dwordx4 v[84:87], v[136:137], off offset:256
	global_load_dwordx4 v[88:91], v[130:131], off offset:256
	global_load_dwordx4 v[92:95], v[128:129], off offset:256
	global_load_dwordx4 v[146:149], v[130:131], off offset:256
	global_load_dwordx4 v[150:153], v[154:155], off offset:256
	global_load_dwordx4 v[156:159], v[130:131], off offset:256
	global_load_dwordx4 v[160:163], v[164:165], off offset:256
	s_waitcnt vmcnt(18) lgkmcnt(3)
	v_pk_fma_f32 v[64:65], v[64:65], v[100:101], v[104:105]
	v_pk_fma_f32 v[66:67], v[66:67], v[102:103], v[106:107]
	global_store_dwordx4 v[98:99], v[64:67], off
	s_waitcnt vmcnt(17) lgkmcnt(2)
	v_pk_fma_f32 v[68:69], v[68:69], v[110:111], v[114:115]
	v_pk_fma_f32 v[70:71], v[70:71], v[112:113], v[116:117]
	global_store_dwordx4 v[108:109], v[68:71], off
	s_waitcnt vmcnt(16) lgkmcnt(1)
	v_pk_fma_f32 v[72:73], v[72:73], v[120:121], v[124:125]
	v_pk_fma_f32 v[74:75], v[74:75], v[122:123], v[126:127]
	global_store_dwordx4 v[118:119], v[72:75], off
	s_waitcnt vmcnt(15) lgkmcnt(0)
	v_pk_fma_f32 v[76:77], v[76:77], v[138:139], v[142:143]
	v_pk_fma_f32 v[78:79], v[78:79], v[140:141], v[144:145]
	global_store_dwordx4 v[96:97], v[76:79], off
	ds_write_b128 v211, v[48:51]
	ds_write_b128 v211, v[52:55] offset:32
	ds_write_b128 v211, v[56:59] offset:64
	ds_write_b128 v211, v[60:63] offset:96
	ds_read_b128 v[48:51], v212
	ds_read_b128 v[52:55], v213
	ds_read_b128 v[56:59], v214
	ds_read_b128 v[60:63], v215
	s_mov_b64 s[2:3], 0x20100
	v_lshl_add_u64 v[64:65], v[134:135], 0, s[2:3]
	v_lshl_add_u64 v[66:67], v[64:65], 0, v[184:185]
	global_load_dwordx4 v[68:71], v[130:131], off offset:256
	global_load_dwordx4 v[72:75], v[66:67], off
	v_lshl_add_u64 v[76:77], v[64:65], 0, v[186:187]
	global_load_dwordx4 v[96:99], v[130:131], off offset:256
	global_load_dwordx4 v[100:103], v[76:77], off
	v_lshl_add_u64 v[78:79], v[64:65], 0, v[188:189]
	global_load_dwordx4 v[104:107], v[130:131], off offset:256
	global_load_dwordx4 v[108:111], v[78:79], off
	v_lshl_add_u64 v[64:65], v[64:65], 0, v[190:191]
	global_load_dwordx4 v[112:115], v[130:131], off offset:256
	global_load_dwordx4 v[116:119], v[64:65], off
	s_waitcnt vmcnt(18) lgkmcnt(3)
	v_pk_fma_f32 v[48:49], v[48:49], v[80:81], v[84:85]
	v_pk_fma_f32 v[50:51], v[50:51], v[82:83], v[86:87]
	global_store_dwordx4 v[136:137], v[48:51], off offset:256
	s_waitcnt vmcnt(17) lgkmcnt(2)
	v_pk_fma_f32 v[52:53], v[52:53], v[88:89], v[92:93]
	v_pk_fma_f32 v[54:55], v[54:55], v[90:91], v[94:95]
	global_store_dwordx4 v[128:129], v[52:55], off offset:256
	s_waitcnt vmcnt(16) lgkmcnt(1)
	v_pk_fma_f32 v[56:57], v[56:57], v[146:147], v[150:151]
	v_pk_fma_f32 v[58:59], v[58:59], v[148:149], v[152:153]
	global_store_dwordx4 v[154:155], v[56:59], off offset:256
	s_waitcnt vmcnt(15) lgkmcnt(0)
	v_pk_fma_f32 v[60:61], v[60:61], v[156:157], v[160:161]
	v_pk_fma_f32 v[62:63], v[62:63], v[158:159], v[162:163]
	global_store_dwordx4 v[164:165], v[60:63], off offset:256
	ds_write_b128 v211, v[32:35]
	ds_write_b128 v211, v[36:39] offset:32
	ds_write_b128 v211, v[40:43] offset:64
	ds_write_b128 v211, v[44:47] offset:96
	ds_read_b128 v[32:35], v212
	ds_read_b128 v[36:39], v213
	ds_read_b128 v[40:43], v214
	ds_read_b128 v[44:47], v215
	global_load_dwordx4 v[48:51], v[130:131], off offset:384
	global_load_dwordx4 v[52:55], v[136:137], off offset:384
	global_load_dwordx4 v[56:59], v[130:131], off offset:384
	global_load_dwordx4 v[60:63], v[128:129], off offset:384
	global_load_dwordx4 v[80:83], v[130:131], off offset:384
	global_load_dwordx4 v[84:87], v[154:155], off offset:384
	global_load_dwordx4 v[88:91], v[130:131], off offset:384
	global_load_dwordx4 v[92:95], v[164:165], off offset:384
	s_waitcnt vmcnt(18) lgkmcnt(3)
	v_pk_fma_f32 v[32:33], v[32:33], v[68:69], v[72:73]
	v_pk_fma_f32 v[34:35], v[34:35], v[70:71], v[74:75]
	global_store_dwordx4 v[66:67], v[32:35], off
	s_waitcnt vmcnt(17) lgkmcnt(2)
	v_pk_fma_f32 v[36:37], v[36:37], v[96:97], v[100:101]
	v_pk_fma_f32 v[38:39], v[38:39], v[98:99], v[102:103]
	global_store_dwordx4 v[76:77], v[36:39], off
	s_waitcnt vmcnt(16) lgkmcnt(1)
	v_pk_fma_f32 v[40:41], v[40:41], v[104:105], v[108:109]
	v_pk_fma_f32 v[42:43], v[42:43], v[106:107], v[110:111]
	global_store_dwordx4 v[78:79], v[40:43], off
	s_waitcnt vmcnt(15) lgkmcnt(0)
	v_pk_fma_f32 v[44:45], v[44:45], v[112:113], v[116:117]
	v_pk_fma_f32 v[46:47], v[46:47], v[114:115], v[118:119]
	global_store_dwordx4 v[64:65], v[44:47], off
	ds_write_b128 v211, v[16:19]
	ds_write_b128 v211, v[20:23] offset:32
	ds_write_b128 v211, v[24:27] offset:64
	ds_write_b128 v211, v[28:31] offset:96
	ds_read_b128 v[16:19], v212
	ds_read_b128 v[20:23], v213
	ds_read_b128 v[24:27], v214
	ds_read_b128 v[28:31], v215
	s_mov_b64 s[2:3], 0x20180
	v_lshl_add_u64 v[32:33], v[134:135], 0, s[2:3]
	v_lshl_add_u64 v[34:35], v[32:33], 0, v[184:185]
	global_load_dwordx4 v[36:39], v[130:131], off offset:384
	global_load_dwordx4 v[40:43], v[34:35], off
	v_lshl_add_u64 v[44:45], v[32:33], 0, v[186:187]
	global_load_dwordx4 v[64:67], v[130:131], off offset:384
	global_load_dwordx4 v[68:71], v[44:45], off
	v_lshl_add_u64 v[46:47], v[32:33], 0, v[188:189]
	global_load_dwordx4 v[72:75], v[130:131], off offset:384
	global_load_dwordx4 v[76:79], v[46:47], off
	v_lshl_add_u64 v[32:33], v[32:33], 0, v[190:191]
	global_load_dwordx4 v[96:99], v[130:131], off offset:384
	global_load_dwordx4 v[100:103], v[32:33], off
	s_waitcnt vmcnt(18) lgkmcnt(3)
	v_pk_fma_f32 v[16:17], v[16:17], v[48:49], v[52:53]
	v_pk_fma_f32 v[18:19], v[18:19], v[50:51], v[54:55]
	global_store_dwordx4 v[136:137], v[16:19], off offset:384
	s_waitcnt vmcnt(17) lgkmcnt(2)
	v_pk_fma_f32 v[20:21], v[20:21], v[56:57], v[60:61]
	v_pk_fma_f32 v[22:23], v[22:23], v[58:59], v[62:63]
	global_store_dwordx4 v[128:129], v[20:23], off offset:384
	s_waitcnt vmcnt(16) lgkmcnt(1)
	v_pk_fma_f32 v[24:25], v[24:25], v[80:81], v[84:85]
	v_pk_fma_f32 v[26:27], v[26:27], v[82:83], v[86:87]
	global_store_dwordx4 v[154:155], v[24:27], off offset:384
	s_waitcnt vmcnt(15) lgkmcnt(0)
	v_pk_fma_f32 v[28:29], v[28:29], v[88:89], v[92:93]
	v_pk_fma_f32 v[30:31], v[30:31], v[90:91], v[94:95]
	global_store_dwordx4 v[164:165], v[28:31], off offset:384
	ds_write_b128 v211, v[0:3]
	ds_write_b128 v211, v[4:7] offset:32
	ds_write_b128 v211, v[8:11] offset:64
	ds_write_b128 v211, v[12:15] offset:96
	ds_read_b128 v[0:3], v212
	ds_read_b128 v[4:7], v213
	ds_read_b128 v[8:11], v214
	ds_read_b128 v[12:15], v215
	s_waitcnt vmcnt(10) lgkmcnt(3)
	v_pk_fma_f32 v[0:1], v[0:1], v[36:37], v[40:41]
	v_pk_fma_f32 v[2:3], v[2:3], v[38:39], v[42:43]
	global_store_dwordx4 v[34:35], v[0:3], off
	s_waitcnt vmcnt(9) lgkmcnt(2)
	v_pk_fma_f32 v[4:5], v[4:5], v[64:65], v[68:69]
	v_pk_fma_f32 v[6:7], v[6:7], v[66:67], v[70:71]
	global_store_dwordx4 v[44:45], v[4:7], off
	s_waitcnt vmcnt(8) lgkmcnt(1)
	v_pk_fma_f32 v[8:9], v[8:9], v[72:73], v[76:77]
	v_pk_fma_f32 v[10:11], v[10:11], v[74:75], v[78:79]
	global_store_dwordx4 v[46:47], v[8:11], off
	s_waitcnt vmcnt(7) lgkmcnt(0)
	v_pk_fma_f32 v[12:13], v[12:13], v[96:97], v[100:101]
	v_pk_fma_f32 v[14:15], v[14:15], v[98:99], v[102:103]
	global_store_dwordx4 v[32:33], v[12:15], off
	s_waitcnt lgkmcnt(0)
	s_barrier
	s_cbranch_scc1 .LBB0_788

.LBB0_1200:
	s_waitcnt lgkmcnt(0)
	s_lshl_b32 s24, s43, 8
	s_add_i32 s50, s24, s35
	s_lshl_b64 s[2:3], s[2:3], s56
	s_lshl_b64 s[54:55], s[54:55], 12
	s_add_u32 s24, s52, s54
	s_addc_u32 s51, s53, s55
	s_lshl_b64 s[2:3], s[2:3], 2
	s_add_u32 s24, s24, s2
	s_addc_u32 s52, s51, s3
	s_ashr_i32 s51, s50, 31
	s_lshl_b64 s[2:3], s[50:51], 2
	s_add_u32 s50, s24, s2
	s_addc_u32 s51, s52, s3
	s_add_u32 s24, s20, s48
	s_addc_u32 s48, s21, s49
	s_add_u32 s2, s24, s2
	s_addc_u32 s3, s48, s3
	v_lshl_add_u64 v[128:129], s[2:3], 0, v[176:177]
	v_lshl_add_u64 v[130:131], s[50:51], 0, v[176:177]
	v_mov_b32_e32 v183, v177
	v_lshl_add_u64 v[132:133], v[130:131], 0, v[182:183]
	v_add_co_u32_e32 v134, vcc, s31, v128
	v_mov_b32_e32 v185, v177
	s_nop 1
	v_addc_co_u32_e32 v135, vcc, 0, v129, vcc
	global_load_dwordx4 v[136:139], v[132:133], off
	global_load_dwordx4 v[140:143], v[134:135], off
	v_lshl_add_u64 v[144:145], v[130:131], 0, v[184:185]
	v_mov_b32_e32 v187, v177
	v_mov_b32_e32 v189, v177
	s_add_i32 s74, s74, 1
	s_cmp_eq_u32 s74, s33
	global_load_dwordx4 v[146:149], v[134:135], off
	global_load_dwordx4 v[150:153], v[144:145], off
	v_lshl_add_u64 v[154:155], v[130:131], 0, v[186:187]
	v_lshl_add_u64 v[156:157], v[130:131], 0, v[188:189]
	global_load_dwordx4 v[158:161], v[134:135], off
	global_load_dwordx4 v[162:165], v[154:155], off
	global_load_dwordx4 v[166:169], v[134:135], off
	global_load_dwordx4 v[170:173], v[156:157], off
	ds_write_b128 v210, v[112:115]
	ds_write_b128 v210, v[116:119] offset:32
	ds_write_b128 v210, v[120:123] offset:64
	ds_write_b128 v210, v[124:127] offset:96
	ds_read_b128 v[112:115], v211
	ds_read_b128 v[116:119], v212
	ds_read_b128 v[120:123], v213
	ds_read_b128 v[124:127], v214
	s_waitcnt vmcnt(6) lgkmcnt(3)
	v_pk_fma_f32 v[112:113], v[112:113], v[140:141], v[136:137]
	v_pk_fma_f32 v[114:115], v[114:115], v[142:143], v[138:139]
	global_store_dwordx4 v[132:133], v[112:115], off
	s_waitcnt vmcnt(5) lgkmcnt(2)
	v_pk_fma_f32 v[146:147], v[116:117], v[146:147], v[150:151]
	v_pk_fma_f32 v[148:149], v[118:119], v[148:149], v[152:153]
	global_store_dwordx4 v[144:145], v[146:149], off
	s_waitcnt vmcnt(4) lgkmcnt(1)
	v_pk_fma_f32 v[158:159], v[120:121], v[158:159], v[162:163]
	v_pk_fma_f32 v[160:161], v[122:123], v[160:161], v[164:165]
	global_store_dwordx4 v[154:155], v[158:161], off
	s_waitcnt vmcnt(3) lgkmcnt(0)
	v_pk_fma_f32 v[166:167], v[124:125], v[166:167], v[170:171]
	v_pk_fma_f32 v[168:169], v[126:127], v[168:169], v[172:173]
	global_store_dwordx4 v[156:157], v[166:169], off
	v_lshl_add_u64 v[112:113], v[130:131], 0, s[8:9]
	v_lshl_add_u64 v[114:115], v[112:113], 0, v[182:183]
	global_load_dwordx4 v[116:119], v[134:135], off
	global_load_dwordx4 v[120:123], v[114:115], off
	v_lshl_add_u64 v[124:125], v[112:113], 0, v[184:185]
	v_lshl_add_u64 v[126:127], v[112:113], 0, v[186:187]
	global_load_dwordx4 v[136:139], v[134:135], off
	global_load_dwordx4 v[140:143], v[124:125], off
	v_lshl_add_u64 v[146:147], v[112:113], 0, v[188:189]
	global_load_dwordx4 v[148:151], v[134:135], off
	global_load_dwordx4 v[158:161], v[126:127], off
	global_load_dwordx4 v[162:165], v[134:135], off
	global_load_dwordx4 v[166:169], v[146:147], off
	ds_write_b128 v210, v[96:99]
	ds_write_b128 v210, v[100:103] offset:32
	ds_write_b128 v210, v[104:107] offset:64
	ds_write_b128 v210, v[108:111] offset:96
	ds_read_b128 v[96:99], v211
	ds_read_b128 v[100:103], v212
	ds_read_b128 v[104:107], v213
	ds_read_b128 v[108:111], v214
	global_load_dwordx4 v[170:173], v[132:133], off offset:128
	v_lshl_add_u64 v[112:113], v[128:129], 0, s[76:77]
	global_load_dwordx4 v[216:219], v[112:113], off offset:128
	global_load_dwordx4 v[220:223], v[112:113], off offset:128
	global_load_dwordx4 v[224:227], v[144:145], off offset:128
	global_load_dwordx4 v[240:243], v[112:113], off offset:128
	global_load_dwordx4 v[244:247], v[154:155], off offset:128
	global_load_dwordx4 v[248:251], v[112:113], off offset:128
	global_load_dwordx4 v[252:255], v[156:157], off offset:128
	s_waitcnt vmcnt(14) lgkmcnt(3)
	v_pk_fma_f32 v[96:97], v[96:97], v[116:117], v[120:121]
	v_pk_fma_f32 v[98:99], v[98:99], v[118:119], v[122:123]
	global_store_dwordx4 v[114:115], v[96:99], off
	s_waitcnt vmcnt(13) lgkmcnt(2)
	v_pk_fma_f32 v[136:137], v[100:101], v[136:137], v[140:141]
	v_pk_fma_f32 v[138:139], v[102:103], v[138:139], v[142:143]
	global_store_dwordx4 v[124:125], v[136:139], off
	s_waitcnt vmcnt(12) lgkmcnt(1)
	v_pk_fma_f32 v[148:149], v[104:105], v[148:149], v[158:159]
	v_pk_fma_f32 v[150:151], v[106:107], v[150:151], v[160:161]
	global_store_dwordx4 v[126:127], v[148:151], off
	s_waitcnt vmcnt(11) lgkmcnt(0)
	v_pk_fma_f32 v[162:163], v[108:109], v[162:163], v[166:167]
	v_pk_fma_f32 v[164:165], v[110:111], v[164:165], v[168:169]
	global_store_dwordx4 v[146:147], v[162:165], off
	ds_write_b128 v210, v[80:83]
	ds_write_b128 v210, v[84:87] offset:32
	ds_write_b128 v210, v[88:91] offset:64
	ds_write_b128 v210, v[92:95] offset:96
	ds_read_b128 v[80:83], v211
	ds_read_b128 v[84:87], v212
	ds_read_b128 v[88:91], v213
	ds_read_b128 v[92:95], v214
	v_lshl_add_u64 v[96:97], v[130:131], 0, s[36:37]
	v_lshl_add_u64 v[98:99], v[96:97], 0, v[182:183]
	global_load_dwordx4 v[100:103], v[112:113], off offset:128
	global_load_dwordx4 v[104:107], v[98:99], off
	v_lshl_add_u64 v[108:109], v[96:97], 0, v[184:185]
	v_lshl_add_u64 v[110:111], v[96:97], 0, v[186:187]
	global_load_dwordx4 v[114:117], v[112:113], off offset:128
	global_load_dwordx4 v[118:121], v[108:109], off
	v_lshl_add_u64 v[122:123], v[96:97], 0, v[188:189]
	global_load_dwordx4 v[124:127], v[112:113], off offset:128
	global_load_dwordx4 v[134:137], v[110:111], off
	global_load_dwordx4 v[138:141], v[112:113], off offset:128
	global_load_dwordx4 v[146:149], v[122:123], off
	s_waitcnt vmcnt(18) lgkmcnt(3)
	v_pk_fma_f32 v[80:81], v[80:81], v[216:217], v[170:171]
	v_pk_fma_f32 v[82:83], v[82:83], v[218:219], v[172:173]
	global_store_dwordx4 v[132:133], v[80:83], off offset:128
	s_waitcnt vmcnt(17) lgkmcnt(2)
	v_pk_fma_f32 v[220:221], v[84:85], v[220:221], v[224:225]
	v_pk_fma_f32 v[222:223], v[86:87], v[222:223], v[226:227]
	global_store_dwordx4 v[144:145], v[220:223], off offset:128
	s_waitcnt vmcnt(16) lgkmcnt(1)
	v_pk_fma_f32 v[240:241], v[88:89], v[240:241], v[244:245]
	v_pk_fma_f32 v[242:243], v[90:91], v[242:243], v[246:247]
	global_store_dwordx4 v[154:155], v[240:243], off offset:128
	s_waitcnt vmcnt(15) lgkmcnt(0)
	v_pk_fma_f32 v[248:249], v[92:93], v[248:249], v[252:253]
	v_pk_fma_f32 v[250:251], v[94:95], v[250:251], v[254:255]
	global_store_dwordx4 v[156:157], v[248:251], off offset:128
	ds_write_b128 v210, v[64:67]
	ds_write_b128 v210, v[68:71] offset:32
	ds_write_b128 v210, v[72:75] offset:64
	ds_write_b128 v210, v[76:79] offset:96
	ds_read_b128 v[64:67], v211
	ds_read_b128 v[68:71], v212
	ds_read_b128 v[72:75], v213
	ds_read_b128 v[76:79], v214
	global_load_dwordx4 v[80:83], v[132:133], off offset:256
	global_load_dwordx4 v[84:87], v[112:113], off offset:256
	global_load_dwordx4 v[88:91], v[112:113], off offset:256
	global_load_dwordx4 v[92:95], v[144:145], off offset:256
	global_load_dwordx4 v[150:153], v[112:113], off offset:256
	global_load_dwordx4 v[158:161], v[154:155], off offset:256
	global_load_dwordx4 v[162:165], v[112:113], off offset:256
	global_load_dwordx4 v[166:169], v[156:157], off offset:256
	s_waitcnt vmcnt(18) lgkmcnt(3)
	v_pk_fma_f32 v[64:65], v[64:65], v[100:101], v[104:105]
	v_pk_fma_f32 v[66:67], v[66:67], v[102:103], v[106:107]
	global_store_dwordx4 v[98:99], v[64:67], off
	s_waitcnt vmcnt(17) lgkmcnt(2)
	v_pk_fma_f32 v[114:115], v[68:69], v[114:115], v[118:119]
	v_pk_fma_f32 v[116:117], v[70:71], v[116:117], v[120:121]
	global_store_dwordx4 v[108:109], v[114:117], off
	s_waitcnt vmcnt(16) lgkmcnt(1)
	v_pk_fma_f32 v[124:125], v[72:73], v[124:125], v[134:135]
	v_pk_fma_f32 v[126:127], v[74:75], v[126:127], v[136:137]
	global_store_dwordx4 v[110:111], v[124:127], off
	s_waitcnt vmcnt(15) lgkmcnt(0)
	v_pk_fma_f32 v[138:139], v[76:77], v[138:139], v[146:147]
	v_pk_fma_f32 v[140:141], v[78:79], v[140:141], v[148:149]
	global_store_dwordx4 v[122:123], v[138:141], off
	ds_write_b128 v210, v[48:51]
	ds_write_b128 v210, v[52:55] offset:32
	ds_write_b128 v210, v[56:59] offset:64
	ds_write_b128 v210, v[60:63] offset:96
	ds_read_b128 v[48:51], v211
	ds_read_b128 v[52:55], v212
	ds_read_b128 v[56:59], v213
	ds_read_b128 v[60:63], v214
	v_lshl_add_u64 v[64:65], v[130:131], 0, s[38:39]
	v_lshl_add_u64 v[66:67], v[64:65], 0, v[182:183]
	global_load_dwordx4 v[68:71], v[112:113], off offset:256
	global_load_dwordx4 v[72:75], v[66:67], off
	v_lshl_add_u64 v[76:77], v[64:65], 0, v[184:185]
	v_lshl_add_u64 v[78:79], v[64:65], 0, v[186:187]
	global_load_dwordx4 v[96:99], v[112:113], off offset:256
	global_load_dwordx4 v[100:103], v[76:77], off
	global_load_dwordx4 v[104:107], v[112:113], off offset:256
	global_load_dwordx4 v[108:111], v[78:79], off
	v_lshl_add_u64 v[114:115], v[64:65], 0, v[188:189]
	global_load_dwordx4 v[116:119], v[112:113], off offset:256
	global_load_dwordx4 v[120:123], v[114:115], off
	s_waitcnt vmcnt(18) lgkmcnt(3)
	v_pk_fma_f32 v[48:49], v[48:49], v[84:85], v[80:81]
	v_pk_fma_f32 v[50:51], v[50:51], v[86:87], v[82:83]
	global_store_dwordx4 v[132:133], v[48:51], off offset:256
	s_waitcnt vmcnt(17) lgkmcnt(2)
	v_pk_fma_f32 v[88:89], v[52:53], v[88:89], v[92:93]
	v_pk_fma_f32 v[90:91], v[54:55], v[90:91], v[94:95]
	global_store_dwordx4 v[144:145], v[88:91], off offset:256
	s_waitcnt vmcnt(16) lgkmcnt(1)
	v_pk_fma_f32 v[150:151], v[56:57], v[150:151], v[158:159]
	v_pk_fma_f32 v[152:153], v[58:59], v[152:153], v[160:161]
	global_store_dwordx4 v[154:155], v[150:153], off offset:256
	s_waitcnt vmcnt(15) lgkmcnt(0)
	v_pk_fma_f32 v[162:163], v[60:61], v[162:163], v[166:167]
	v_pk_fma_f32 v[164:165], v[62:63], v[164:165], v[168:169]
	global_store_dwordx4 v[156:157], v[162:165], off offset:256
	ds_write_b128 v210, v[32:35]
	ds_write_b128 v210, v[36:39] offset:32
	ds_write_b128 v210, v[40:43] offset:64
	ds_write_b128 v210, v[44:47] offset:96
	ds_read_b128 v[32:35], v211
	ds_read_b128 v[36:39], v212
	ds_read_b128 v[40:43], v213
	ds_read_b128 v[44:47], v214
	global_load_dwordx4 v[48:51], v[132:133], off offset:384
	global_load_dwordx4 v[52:55], v[112:113], off offset:384
	global_load_dwordx4 v[56:59], v[112:113], off offset:384
	global_load_dwordx4 v[60:63], v[144:145], off offset:384
	global_load_dwordx4 v[80:83], v[112:113], off offset:384
	global_load_dwordx4 v[84:87], v[154:155], off offset:384
	global_load_dwordx4 v[88:91], v[112:113], off offset:384
	global_load_dwordx4 v[92:95], v[156:157], off offset:384
	s_waitcnt vmcnt(18) lgkmcnt(3)
	v_pk_fma_f32 v[32:33], v[32:33], v[68:69], v[72:73]
	v_pk_fma_f32 v[34:35], v[34:35], v[70:71], v[74:75]
	global_store_dwordx4 v[66:67], v[32:35], off
	s_waitcnt vmcnt(17) lgkmcnt(2)
	v_pk_fma_f32 v[96:97], v[36:37], v[96:97], v[100:101]
	v_pk_fma_f32 v[98:99], v[38:39], v[98:99], v[102:103]
	global_store_dwordx4 v[76:77], v[96:99], off
	s_waitcnt vmcnt(16) lgkmcnt(1)
	v_pk_fma_f32 v[104:105], v[40:41], v[104:105], v[108:109]
	v_pk_fma_f32 v[106:107], v[42:43], v[106:107], v[110:111]
	global_store_dwordx4 v[78:79], v[104:107], off
	s_waitcnt vmcnt(15) lgkmcnt(0)
	v_pk_fma_f32 v[116:117], v[44:45], v[116:117], v[120:121]
	v_pk_fma_f32 v[118:119], v[46:47], v[118:119], v[122:123]
	global_store_dwordx4 v[114:115], v[116:119], off
	ds_write_b128 v210, v[16:19]
	ds_write_b128 v210, v[20:23] offset:32
	ds_write_b128 v210, v[24:27] offset:64
	ds_write_b128 v210, v[28:31] offset:96
	ds_read_b128 v[16:19], v211
	ds_read_b128 v[20:23], v212
	ds_read_b128 v[24:27], v213
	ds_read_b128 v[28:31], v214
	v_lshl_add_u64 v[32:33], v[130:131], 0, s[40:41]
	v_lshl_add_u64 v[34:35], v[32:33], 0, v[182:183]
	global_load_dwordx4 v[36:39], v[112:113], off offset:384
	global_load_dwordx4 v[40:43], v[34:35], off
	v_lshl_add_u64 v[44:45], v[32:33], 0, v[184:185]
	v_lshl_add_u64 v[46:47], v[32:33], 0, v[186:187]
	global_load_dwordx4 v[64:67], v[112:113], off offset:384
	global_load_dwordx4 v[68:71], v[44:45], off
	global_load_dwordx4 v[72:75], v[112:113], off offset:384
	global_load_dwordx4 v[76:79], v[46:47], off
	v_lshl_add_u64 v[96:97], v[32:33], 0, v[188:189]
	global_load_dwordx4 v[98:101], v[112:113], off offset:384
	global_load_dwordx4 v[102:105], v[96:97], off
	s_waitcnt vmcnt(18) lgkmcnt(3)
	v_pk_fma_f32 v[16:17], v[16:17], v[52:53], v[48:49]
	v_pk_fma_f32 v[18:19], v[18:19], v[54:55], v[50:51]
	global_store_dwordx4 v[132:133], v[16:19], off offset:384
	s_waitcnt vmcnt(17) lgkmcnt(2)
	v_pk_fma_f32 v[56:57], v[20:21], v[56:57], v[60:61]
	v_pk_fma_f32 v[58:59], v[22:23], v[58:59], v[62:63]
	global_store_dwordx4 v[144:145], v[56:59], off offset:384
	s_waitcnt vmcnt(16) lgkmcnt(1)
	v_pk_fma_f32 v[80:81], v[24:25], v[80:81], v[84:85]
	v_pk_fma_f32 v[82:83], v[26:27], v[82:83], v[86:87]
	global_store_dwordx4 v[154:155], v[80:83], off offset:384
	s_waitcnt vmcnt(15) lgkmcnt(0)
	v_pk_fma_f32 v[88:89], v[28:29], v[88:89], v[92:93]
	v_pk_fma_f32 v[90:91], v[30:31], v[90:91], v[94:95]
	global_store_dwordx4 v[156:157], v[88:91], off offset:384
	ds_write_b128 v210, v[0:3]
	ds_write_b128 v210, v[4:7] offset:32
	ds_write_b128 v210, v[8:11] offset:64
	ds_write_b128 v210, v[12:15] offset:96
	ds_read_b128 v[0:3], v211
	ds_read_b128 v[4:7], v212
	ds_read_b128 v[8:11], v213
	ds_read_b128 v[12:15], v214
	s_waitcnt vmcnt(10) lgkmcnt(3)
	v_pk_fma_f32 v[0:1], v[0:1], v[36:37], v[40:41]
	v_pk_fma_f32 v[2:3], v[2:3], v[38:39], v[42:43]
	global_store_dwordx4 v[34:35], v[0:3], off
	s_waitcnt vmcnt(9) lgkmcnt(2)
	v_pk_fma_f32 v[64:65], v[4:5], v[64:65], v[68:69]
	v_pk_fma_f32 v[66:67], v[6:7], v[66:67], v[70:71]
	global_store_dwordx4 v[44:45], v[64:67], off
	s_waitcnt vmcnt(8) lgkmcnt(1)
	v_pk_fma_f32 v[72:73], v[8:9], v[72:73], v[76:77]
	v_pk_fma_f32 v[74:75], v[10:11], v[74:75], v[78:79]
	global_store_dwordx4 v[46:47], v[72:75], off
	s_waitcnt vmcnt(7) lgkmcnt(0)
	v_pk_fma_f32 v[98:99], v[12:13], v[98:99], v[102:103]
	v_pk_fma_f32 v[100:101], v[14:15], v[100:101], v[104:105]
	global_store_dwordx4 v[96:97], v[98:101], off
	s_waitcnt lgkmcnt(0)
	s_barrier
	s_cbranch_scc1 .LBB0_1256

.LBB0_1519:
	s_waitcnt lgkmcnt(0)
	s_lshl_b32 s18, s41, 8
	s_add_i32 s48, s18, s35
	s_lshl_b64 s[2:3], s[2:3], s54
	s_lshl_b64 s[52:53], s[52:53], 12
	s_add_u32 s18, s50, s52
	s_addc_u32 s49, s51, s53
	s_lshl_b64 s[2:3], s[2:3], 2
	s_add_u32 s18, s18, s2
	s_addc_u32 s50, s49, s3
	s_ashr_i32 s49, s48, 31
	s_lshl_b64 s[2:3], s[48:49], 2
	s_add_u32 s48, s18, s2
	s_addc_u32 s49, s50, s3
	s_add_u32 s18, s20, s42
	s_addc_u32 s42, s21, s43
	s_add_u32 s2, s18, s2
	s_addc_u32 s3, s42, s3
	v_lshl_add_u64 v[128:129], s[2:3], 0, v[176:177]
	v_lshl_add_u64 v[130:131], s[48:49], 0, v[176:177]
	v_mov_b32_e32 v183, v177
	v_lshl_add_u64 v[132:133], v[130:131], 0, v[182:183]
	v_add_co_u32_e32 v134, vcc, s71, v128
	v_mov_b32_e32 v185, v177
	s_nop 1
	v_addc_co_u32_e32 v135, vcc, 0, v129, vcc
	global_load_dwordx4 v[136:139], v[132:133], off
	global_load_dwordx4 v[140:143], v[134:135], off
	v_lshl_add_u64 v[144:145], v[130:131], 0, v[184:185]
	v_mov_b32_e32 v187, v177
	v_mov_b32_e32 v189, v177
	s_add_i32 s73, s73, 1
	s_cmp_eq_u32 s73, s33
	global_load_dwordx4 v[146:149], v[134:135], off
	global_load_dwordx4 v[150:153], v[144:145], off
	v_lshl_add_u64 v[154:155], v[130:131], 0, v[186:187]
	v_lshl_add_u64 v[156:157], v[130:131], 0, v[188:189]
	global_load_dwordx4 v[158:161], v[134:135], off
	global_load_dwordx4 v[162:165], v[154:155], off
	global_load_dwordx4 v[166:169], v[134:135], off
	global_load_dwordx4 v[170:173], v[156:157], off
	ds_write_b128 v210, v[112:115]
	ds_write_b128 v210, v[116:119] offset:32
	ds_write_b128 v210, v[120:123] offset:64
	ds_write_b128 v210, v[124:127] offset:96
	ds_read_b128 v[112:115], v211
	ds_read_b128 v[116:119], v212
	ds_read_b128 v[120:123], v213
	ds_read_b128 v[124:127], v214
	s_waitcnt vmcnt(6) lgkmcnt(3)
	v_pk_fma_f32 v[112:113], v[112:113], v[140:141], v[136:137]
	v_pk_fma_f32 v[114:115], v[114:115], v[142:143], v[138:139]
	global_store_dwordx4 v[132:133], v[112:115], off
	s_waitcnt vmcnt(5) lgkmcnt(2)
	v_pk_fma_f32 v[146:147], v[116:117], v[146:147], v[150:151]
	v_pk_fma_f32 v[148:149], v[118:119], v[148:149], v[152:153]
	global_store_dwordx4 v[144:145], v[146:149], off
	s_waitcnt vmcnt(4) lgkmcnt(1)
	v_pk_fma_f32 v[158:159], v[120:121], v[158:159], v[162:163]
	v_pk_fma_f32 v[160:161], v[122:123], v[160:161], v[164:165]
	global_store_dwordx4 v[154:155], v[158:161], off
	s_waitcnt vmcnt(3) lgkmcnt(0)
	v_pk_fma_f32 v[166:167], v[124:125], v[166:167], v[170:171]
	v_pk_fma_f32 v[168:169], v[126:127], v[168:169], v[172:173]
	global_store_dwordx4 v[156:157], v[166:169], off
	v_lshl_add_u64 v[112:113], v[130:131], 0, s[24:25]
	v_lshl_add_u64 v[114:115], v[112:113], 0, v[182:183]
	global_load_dwordx4 v[116:119], v[134:135], off
	global_load_dwordx4 v[120:123], v[114:115], off
	v_lshl_add_u64 v[124:125], v[112:113], 0, v[184:185]
	v_lshl_add_u64 v[126:127], v[112:113], 0, v[186:187]
	global_load_dwordx4 v[136:139], v[134:135], off
	global_load_dwordx4 v[140:143], v[124:125], off
	v_lshl_add_u64 v[146:147], v[112:113], 0, v[188:189]
	global_load_dwordx4 v[148:151], v[134:135], off
	global_load_dwordx4 v[158:161], v[126:127], off
	global_load_dwordx4 v[162:165], v[134:135], off
	global_load_dwordx4 v[166:169], v[146:147], off
	ds_write_b128 v210, v[96:99]
	ds_write_b128 v210, v[100:103] offset:32
	ds_write_b128 v210, v[104:107] offset:64
	ds_write_b128 v210, v[108:111] offset:96
	ds_read_b128 v[96:99], v211
	ds_read_b128 v[100:103], v212
	ds_read_b128 v[104:107], v213
	ds_read_b128 v[108:111], v214
	global_load_dwordx4 v[170:173], v[132:133], off offset:128
	v_lshl_add_u64 v[112:113], v[128:129], 0, s[76:77]
	global_load_dwordx4 v[216:219], v[112:113], off offset:128
	global_load_dwordx4 v[220:223], v[112:113], off offset:128
	global_load_dwordx4 v[224:227], v[144:145], off offset:128
	global_load_dwordx4 v[240:243], v[112:113], off offset:128
	global_load_dwordx4 v[244:247], v[154:155], off offset:128
	global_load_dwordx4 v[248:251], v[112:113], off offset:128
	global_load_dwordx4 v[252:255], v[156:157], off offset:128
	s_waitcnt vmcnt(14) lgkmcnt(3)
	v_pk_fma_f32 v[96:97], v[96:97], v[116:117], v[120:121]
	v_pk_fma_f32 v[98:99], v[98:99], v[118:119], v[122:123]
	global_store_dwordx4 v[114:115], v[96:99], off
	s_waitcnt vmcnt(13) lgkmcnt(2)
	v_pk_fma_f32 v[136:137], v[100:101], v[136:137], v[140:141]
	v_pk_fma_f32 v[138:139], v[102:103], v[138:139], v[142:143]
	global_store_dwordx4 v[124:125], v[136:139], off
	s_waitcnt vmcnt(12) lgkmcnt(1)
	v_pk_fma_f32 v[148:149], v[104:105], v[148:149], v[158:159]
	v_pk_fma_f32 v[150:151], v[106:107], v[150:151], v[160:161]
	global_store_dwordx4 v[126:127], v[148:151], off
	s_waitcnt vmcnt(11) lgkmcnt(0)
	v_pk_fma_f32 v[162:163], v[108:109], v[162:163], v[166:167]
	v_pk_fma_f32 v[164:165], v[110:111], v[164:165], v[168:169]
	global_store_dwordx4 v[146:147], v[162:165], off
	ds_write_b128 v210, v[80:83]
	ds_write_b128 v210, v[84:87] offset:32
	ds_write_b128 v210, v[88:91] offset:64
	ds_write_b128 v210, v[92:95] offset:96
	ds_read_b128 v[80:83], v211
	ds_read_b128 v[84:87], v212
	ds_read_b128 v[88:91], v213
	ds_read_b128 v[92:95], v214
	v_lshl_add_u64 v[96:97], v[130:131], 0, s[30:31]
	v_lshl_add_u64 v[98:99], v[96:97], 0, v[182:183]
	global_load_dwordx4 v[100:103], v[112:113], off offset:128
	global_load_dwordx4 v[104:107], v[98:99], off
	v_lshl_add_u64 v[108:109], v[96:97], 0, v[184:185]
	v_lshl_add_u64 v[110:111], v[96:97], 0, v[186:187]
	global_load_dwordx4 v[114:117], v[112:113], off offset:128
	global_load_dwordx4 v[118:121], v[108:109], off
	v_lshl_add_u64 v[122:123], v[96:97], 0, v[188:189]
	global_load_dwordx4 v[124:127], v[112:113], off offset:128
	global_load_dwordx4 v[134:137], v[110:111], off
	global_load_dwordx4 v[138:141], v[112:113], off offset:128
	global_load_dwordx4 v[146:149], v[122:123], off
	s_waitcnt vmcnt(18) lgkmcnt(3)
	v_pk_fma_f32 v[80:81], v[80:81], v[216:217], v[170:171]
	v_pk_fma_f32 v[82:83], v[82:83], v[218:219], v[172:173]
	global_store_dwordx4 v[132:133], v[80:83], off offset:128
	s_waitcnt vmcnt(17) lgkmcnt(2)
	v_pk_fma_f32 v[220:221], v[84:85], v[220:221], v[224:225]
	v_pk_fma_f32 v[222:223], v[86:87], v[222:223], v[226:227]
	global_store_dwordx4 v[144:145], v[220:223], off offset:128
	s_waitcnt vmcnt(16) lgkmcnt(1)
	v_pk_fma_f32 v[240:241], v[88:89], v[240:241], v[244:245]
	v_pk_fma_f32 v[242:243], v[90:91], v[242:243], v[246:247]
	global_store_dwordx4 v[154:155], v[240:243], off offset:128
	s_waitcnt vmcnt(15) lgkmcnt(0)
	v_pk_fma_f32 v[248:249], v[92:93], v[248:249], v[252:253]
	v_pk_fma_f32 v[250:251], v[94:95], v[250:251], v[254:255]
	global_store_dwordx4 v[156:157], v[248:251], off offset:128
	ds_write_b128 v210, v[64:67]
	ds_write_b128 v210, v[68:71] offset:32
	ds_write_b128 v210, v[72:75] offset:64
	ds_write_b128 v210, v[76:79] offset:96
	ds_read_b128 v[64:67], v211
	ds_read_b128 v[68:71], v212
	ds_read_b128 v[72:75], v213
	ds_read_b128 v[76:79], v214
	global_load_dwordx4 v[80:83], v[132:133], off offset:256
	global_load_dwordx4 v[84:87], v[112:113], off offset:256
	global_load_dwordx4 v[88:91], v[112:113], off offset:256
	global_load_dwordx4 v[92:95], v[144:145], off offset:256
	global_load_dwordx4 v[150:153], v[112:113], off offset:256
	global_load_dwordx4 v[158:161], v[154:155], off offset:256
	global_load_dwordx4 v[162:165], v[112:113], off offset:256
	global_load_dwordx4 v[166:169], v[156:157], off offset:256
	s_waitcnt vmcnt(18) lgkmcnt(3)
	v_pk_fma_f32 v[64:65], v[64:65], v[100:101], v[104:105]
	v_pk_fma_f32 v[66:67], v[66:67], v[102:103], v[106:107]
	global_store_dwordx4 v[98:99], v[64:67], off
	s_waitcnt vmcnt(17) lgkmcnt(2)
	v_pk_fma_f32 v[114:115], v[68:69], v[114:115], v[118:119]
	v_pk_fma_f32 v[116:117], v[70:71], v[116:117], v[120:121]
	global_store_dwordx4 v[108:109], v[114:117], off
	s_waitcnt vmcnt(16) lgkmcnt(1)
	v_pk_fma_f32 v[124:125], v[72:73], v[124:125], v[134:135]
	v_pk_fma_f32 v[126:127], v[74:75], v[126:127], v[136:137]
	global_store_dwordx4 v[110:111], v[124:127], off
	s_waitcnt vmcnt(15) lgkmcnt(0)
	v_pk_fma_f32 v[138:139], v[76:77], v[138:139], v[146:147]
	v_pk_fma_f32 v[140:141], v[78:79], v[140:141], v[148:149]
	global_store_dwordx4 v[122:123], v[138:141], off
	ds_write_b128 v210, v[48:51]
	ds_write_b128 v210, v[52:55] offset:32
	ds_write_b128 v210, v[56:59] offset:64
	ds_write_b128 v210, v[60:63] offset:96
	ds_read_b128 v[48:51], v211
	ds_read_b128 v[52:55], v212
	ds_read_b128 v[56:59], v213
	ds_read_b128 v[60:63], v214
	v_lshl_add_u64 v[64:65], v[130:131], 0, s[36:37]
	v_lshl_add_u64 v[66:67], v[64:65], 0, v[182:183]
	global_load_dwordx4 v[68:71], v[112:113], off offset:256
	global_load_dwordx4 v[72:75], v[66:67], off
	v_lshl_add_u64 v[76:77], v[64:65], 0, v[184:185]
	v_lshl_add_u64 v[78:79], v[64:65], 0, v[186:187]
	global_load_dwordx4 v[96:99], v[112:113], off offset:256
	global_load_dwordx4 v[100:103], v[76:77], off
	global_load_dwordx4 v[104:107], v[112:113], off offset:256
	global_load_dwordx4 v[108:111], v[78:79], off
	v_lshl_add_u64 v[114:115], v[64:65], 0, v[188:189]
	global_load_dwordx4 v[116:119], v[112:113], off offset:256
	global_load_dwordx4 v[120:123], v[114:115], off
	s_waitcnt vmcnt(18) lgkmcnt(3)
	v_pk_fma_f32 v[48:49], v[48:49], v[84:85], v[80:81]
	v_pk_fma_f32 v[50:51], v[50:51], v[86:87], v[82:83]
	global_store_dwordx4 v[132:133], v[48:51], off offset:256
	s_waitcnt vmcnt(17) lgkmcnt(2)
	v_pk_fma_f32 v[88:89], v[52:53], v[88:89], v[92:93]
	v_pk_fma_f32 v[90:91], v[54:55], v[90:91], v[94:95]
	global_store_dwordx4 v[144:145], v[88:91], off offset:256
	s_waitcnt vmcnt(16) lgkmcnt(1)
	v_pk_fma_f32 v[150:151], v[56:57], v[150:151], v[158:159]
	v_pk_fma_f32 v[152:153], v[58:59], v[152:153], v[160:161]
	global_store_dwordx4 v[154:155], v[150:153], off offset:256
	s_waitcnt vmcnt(15) lgkmcnt(0)
	v_pk_fma_f32 v[162:163], v[60:61], v[162:163], v[166:167]
	v_pk_fma_f32 v[164:165], v[62:63], v[164:165], v[168:169]
	global_store_dwordx4 v[156:157], v[162:165], off offset:256
	ds_write_b128 v210, v[32:35]
	ds_write_b128 v210, v[36:39] offset:32
	ds_write_b128 v210, v[40:43] offset:64
	ds_write_b128 v210, v[44:47] offset:96
	ds_read_b128 v[32:35], v211
	ds_read_b128 v[36:39], v212
	ds_read_b128 v[40:43], v213
	ds_read_b128 v[44:47], v214
	global_load_dwordx4 v[48:51], v[132:133], off offset:384
	global_load_dwordx4 v[52:55], v[112:113], off offset:384
	global_load_dwordx4 v[56:59], v[112:113], off offset:384
	global_load_dwordx4 v[60:63], v[144:145], off offset:384
	global_load_dwordx4 v[80:83], v[112:113], off offset:384
	global_load_dwordx4 v[84:87], v[154:155], off offset:384
	global_load_dwordx4 v[88:91], v[112:113], off offset:384
	global_load_dwordx4 v[92:95], v[156:157], off offset:384
	s_waitcnt vmcnt(18) lgkmcnt(3)
	v_pk_fma_f32 v[32:33], v[32:33], v[68:69], v[72:73]
	v_pk_fma_f32 v[34:35], v[34:35], v[70:71], v[74:75]
	global_store_dwordx4 v[66:67], v[32:35], off
	s_waitcnt vmcnt(17) lgkmcnt(2)
	v_pk_fma_f32 v[96:97], v[36:37], v[96:97], v[100:101]
	v_pk_fma_f32 v[98:99], v[38:39], v[98:99], v[102:103]
	global_store_dwordx4 v[76:77], v[96:99], off
	s_waitcnt vmcnt(16) lgkmcnt(1)
	v_pk_fma_f32 v[104:105], v[40:41], v[104:105], v[108:109]
	v_pk_fma_f32 v[106:107], v[42:43], v[106:107], v[110:111]
	global_store_dwordx4 v[78:79], v[104:107], off
	s_waitcnt vmcnt(15) lgkmcnt(0)
	v_pk_fma_f32 v[116:117], v[44:45], v[116:117], v[120:121]
	v_pk_fma_f32 v[118:119], v[46:47], v[118:119], v[122:123]
	global_store_dwordx4 v[114:115], v[116:119], off
	ds_write_b128 v210, v[16:19]
	ds_write_b128 v210, v[20:23] offset:32
	ds_write_b128 v210, v[24:27] offset:64
	ds_write_b128 v210, v[28:31] offset:96
	ds_read_b128 v[16:19], v211
	ds_read_b128 v[20:23], v212
	ds_read_b128 v[24:27], v213
	ds_read_b128 v[28:31], v214
	v_lshl_add_u64 v[32:33], v[130:131], 0, s[38:39]
	v_lshl_add_u64 v[34:35], v[32:33], 0, v[182:183]
	global_load_dwordx4 v[36:39], v[112:113], off offset:384
	global_load_dwordx4 v[40:43], v[34:35], off
	v_lshl_add_u64 v[44:45], v[32:33], 0, v[184:185]
	v_lshl_add_u64 v[46:47], v[32:33], 0, v[186:187]
	global_load_dwordx4 v[64:67], v[112:113], off offset:384
	global_load_dwordx4 v[68:71], v[44:45], off
	global_load_dwordx4 v[72:75], v[112:113], off offset:384
	global_load_dwordx4 v[76:79], v[46:47], off
	v_lshl_add_u64 v[96:97], v[32:33], 0, v[188:189]
	global_load_dwordx4 v[98:101], v[112:113], off offset:384
	global_load_dwordx4 v[102:105], v[96:97], off
	s_waitcnt vmcnt(18) lgkmcnt(3)
	v_pk_fma_f32 v[16:17], v[16:17], v[52:53], v[48:49]
	v_pk_fma_f32 v[18:19], v[18:19], v[54:55], v[50:51]
	global_store_dwordx4 v[132:133], v[16:19], off offset:384
	s_waitcnt vmcnt(17) lgkmcnt(2)
	v_pk_fma_f32 v[56:57], v[20:21], v[56:57], v[60:61]
	v_pk_fma_f32 v[58:59], v[22:23], v[58:59], v[62:63]
	global_store_dwordx4 v[144:145], v[56:59], off offset:384
	s_waitcnt vmcnt(16) lgkmcnt(1)
	v_pk_fma_f32 v[80:81], v[24:25], v[80:81], v[84:85]
	v_pk_fma_f32 v[82:83], v[26:27], v[82:83], v[86:87]
	global_store_dwordx4 v[154:155], v[80:83], off offset:384
	s_waitcnt vmcnt(15) lgkmcnt(0)
	v_pk_fma_f32 v[88:89], v[28:29], v[88:89], v[92:93]
	v_pk_fma_f32 v[90:91], v[30:31], v[90:91], v[94:95]
	global_store_dwordx4 v[156:157], v[88:91], off offset:384
	ds_write_b128 v210, v[0:3]
	ds_write_b128 v210, v[4:7] offset:32
	ds_write_b128 v210, v[8:11] offset:64
	ds_write_b128 v210, v[12:15] offset:96
	ds_read_b128 v[0:3], v211
	ds_read_b128 v[4:7], v212
	ds_read_b128 v[8:11], v213
	ds_read_b128 v[12:15], v214
	s_waitcnt vmcnt(10) lgkmcnt(3)
	v_pk_fma_f32 v[0:1], v[0:1], v[36:37], v[40:41]
	v_pk_fma_f32 v[2:3], v[2:3], v[38:39], v[42:43]
	global_store_dwordx4 v[34:35], v[0:3], off
	s_waitcnt vmcnt(9) lgkmcnt(2)
	v_pk_fma_f32 v[64:65], v[4:5], v[64:65], v[68:69]
	v_pk_fma_f32 v[66:67], v[6:7], v[66:67], v[70:71]
	global_store_dwordx4 v[44:45], v[64:67], off
	s_waitcnt vmcnt(8) lgkmcnt(1)
	v_pk_fma_f32 v[72:73], v[8:9], v[72:73], v[76:77]
	v_pk_fma_f32 v[74:75], v[10:11], v[74:75], v[78:79]
	global_store_dwordx4 v[46:47], v[72:75], off
	s_waitcnt vmcnt(7) lgkmcnt(0)
	v_pk_fma_f32 v[98:99], v[12:13], v[98:99], v[102:103]
	v_pk_fma_f32 v[100:101], v[14:15], v[100:101], v[104:105]
	global_store_dwordx4 v[96:97], v[98:101], off
	s_waitcnt lgkmcnt(0)
	s_barrier
	s_cbranch_scc1 .LBB0_1575
